# as v45 plus the four GEMM K-loop heads and the attention main-loop head aligned to 64 bytes (s_nop padding)
# baseline (speedup 1.0000x reference)
; template <class Epi, class Sched, bool ALIGN_EPI = false, bool SP2 = false>
; __device__ __forceinline__ void gemm_phase(PG8_LAS unsigned char* lds, const Gemm g, const Sched& S, const Epi& E) {
;     ...
;         const bool has_next = S.next(ui + 1, nxt);
;         const char* nA = has_next ? (const char*)g.A + (size_t)nxt.pm * tstep : cA; const char* nB = has_next ? (const char*)g.Bt + (size_t)nxt.pn * tstep : cB;
;     ...
; #pragma unroll
;         for (int a = 0; a < 2; ++a)
; #pragma unroll
;             for (int b = 0; b < 2; ++b)
; #pragma unroll
;                 for (int m = 0; m < 4; ++m)
; #pragma unroll
;                     for (int n = 0; n < 2; ++n) acc[a][b][m][n] = (f32x4){0.f, 0.f, 0.f, 0.f};
;         cur = nxt; cA = nA; cB = nB; ++ui;
.LBB0_179:
	s_ashr_i32 s87, s86, 31
	s_lshl_b64 s[0:1], s[86:87], 19
	s_add_u32 s78, s89, s0
	s_addc_u32 s79, s83, s1
	s_and_b64 s[0:1], s[42:43], exec
	s_cselect_b32 s0, s79, s45
	s_cselect_b32 s1, s78, s44
	s_ashr_i32 s39, s38, 31
	s_lshl_b64 s[4:5], s[38:39], 19
	s_add_u32 s94, s92, s4
	s_addc_u32 s95, s93, s5
	s_and_b64 s[4:5], s[42:43], exec
	s_cselect_b32 s4, s95, s51
	s_cselect_b32 s5, s94, s50
	s_add_u32 s44, s44, 0x40080
	s_addc_u32 s45, s45, 0
	s_add_u32 s39, s50, 0x100
	v_mov_b32_e32 v0, 0
	s_addc_u32 s57, s51, 0
	s_mov_b32 s71, -2
	v_mov_b32_e32 v1, v0
	v_mov_b32_e32 v2, v0
	v_mov_b32_e32 v3, v0
	v_mov_b32_e32 v24, v0
	v_mov_b32_e32 v25, v0
	v_mov_b32_e32 v26, v0
	v_mov_b32_e32 v27, v0
	v_mov_b32_e32 v64, v0
	v_mov_b32_e32 v65, v0
	v_mov_b32_e32 v66, v0
	v_mov_b32_e32 v67, v0
	v_mov_b32_e32 v128, v0
	v_mov_b32_e32 v129, v0
	v_mov_b32_e32 v130, v0
	v_mov_b32_e32 v131, v0
	v_mov_b32_e32 v32, v0
	v_mov_b32_e32 v33, v0
	v_mov_b32_e32 v34, v0
	v_mov_b32_e32 v35, v0
	v_mov_b32_e32 v12, v0
	v_mov_b32_e32 v13, v0
	v_mov_b32_e32 v14, v0
	v_mov_b32_e32 v15, v0
	v_mov_b32_e32 v4, v0
	v_mov_b32_e32 v5, v0
	v_mov_b32_e32 v6, v0
	v_mov_b32_e32 v7, v0
	v_mov_b32_e32 v8, v0
	v_mov_b32_e32 v9, v0
	v_mov_b32_e32 v10, v0
	v_mov_b32_e32 v11, v0
	v_mov_b32_e32 v16, v0
	v_mov_b32_e32 v17, v0
	v_mov_b32_e32 v18, v0
	v_mov_b32_e32 v19, v0
	v_mov_b32_e32 v20, v0
	v_mov_b32_e32 v21, v0
	v_mov_b32_e32 v22, v0
	v_mov_b32_e32 v23, v0
	v_mov_b32_e32 v28, v0
	v_mov_b32_e32 v29, v0
	v_mov_b32_e32 v30, v0
	v_mov_b32_e32 v31, v0
	v_mov_b32_e32 v40, v0
	v_mov_b32_e32 v41, v0
	v_mov_b32_e32 v42, v0
	v_mov_b32_e32 v43, v0
	v_mov_b32_e32 v48, v0
	v_mov_b32_e32 v49, v0
	v_mov_b32_e32 v50, v0
	v_mov_b32_e32 v51, v0
	v_mov_b32_e32 v56, v0
	v_mov_b32_e32 v57, v0
	v_mov_b32_e32 v58, v0
	v_mov_b32_e32 v59, v0
	v_mov_b32_e32 v36, v0
	v_mov_b32_e32 v37, v0
	v_mov_b32_e32 v38, v0
	v_mov_b32_e32 v39, v0
	v_mov_b32_e32 v44, v0
	v_mov_b32_e32 v45, v0
	v_mov_b32_e32 v46, v0
	v_mov_b32_e32 v47, v0
	v_mov_b32_e32 v52, v0
	v_mov_b32_e32 v53, v0
	v_mov_b32_e32 v54, v0
	v_mov_b32_e32 v55, v0
	v_mov_b32_e32 v60, v0
	v_mov_b32_e32 v61, v0
	v_mov_b32_e32 v62, v0
	v_mov_b32_e32 v63, v0
	v_mov_b32_e32 v68, v0
	v_mov_b32_e32 v69, v0
	v_mov_b32_e32 v70, v0
	v_mov_b32_e32 v71, v0
	v_mov_b32_e32 v72, v0
	v_mov_b32_e32 v73, v0
	v_mov_b32_e32 v74, v0
	v_mov_b32_e32 v75, v0
	v_mov_b32_e32 v96, v0
	v_mov_b32_e32 v97, v0
	v_mov_b32_e32 v98, v0
	v_mov_b32_e32 v99, v0
	v_mov_b32_e32 v104, v0
	v_mov_b32_e32 v105, v0
	v_mov_b32_e32 v106, v0
	v_mov_b32_e32 v107, v0
	v_mov_b32_e32 v132, v0
	v_mov_b32_e32 v133, v0
	v_mov_b32_e32 v134, v0
	v_mov_b32_e32 v135, v0
	v_mov_b32_e32 v136, v0
	v_mov_b32_e32 v137, v0
	v_mov_b32_e32 v138, v0
	v_mov_b32_e32 v139, v0
	v_mov_b32_e32 v140, v0
	v_mov_b32_e32 v141, v0
	v_mov_b32_e32 v142, v0
	v_mov_b32_e32 v143, v0
	v_mov_b32_e32 v144, v0
	v_mov_b32_e32 v145, v0
	v_mov_b32_e32 v146, v0
	v_mov_b32_e32 v147, v0
	v_mov_b32_e32 v112, v0
	v_mov_b32_e32 v113, v0
	v_mov_b32_e32 v114, v0
	v_mov_b32_e32 v115, v0
	v_mov_b32_e32 v120, v0
	v_mov_b32_e32 v121, v0
	v_mov_b32_e32 v122, v0
	v_mov_b32_e32 v123, v0
	v_mov_b32_e32 v124, v0
	v_mov_b32_e32 v125, v0
	v_mov_b32_e32 v126, v0
	v_mov_b32_e32 v127, v0
	v_mov_b32_e32 v148, v0
	v_mov_b32_e32 v149, v0
	v_mov_b32_e32 v150, v0
	v_mov_b32_e32 v151, v0
	v_mov_b32_e32 v152, v0
	v_mov_b32_e32 v153, v0
	v_mov_b32_e32 v154, v0
	v_mov_b32_e32 v155, v0
	v_mov_b32_e32 v156, v0
	v_mov_b32_e32 v157, v0
	v_mov_b32_e32 v158, v0
	v_mov_b32_e32 v159, v0
	.p2alignl 6, 3212836864

;   #define DMA_K(t,slot) glds16(ksrc+(long)(t)*KVBLK*PQ,(unsigned)__builtin_amdgcn_readfirstlane(kdst+(slot)))
;   #define DMA_V(t,slot) glds16(vsrc+(long)(t)*KVBLK*PQ,(unsigned)__builtin_amdgcn_readfirstlane(vdst+(slot)))
; template<int THRL> __device__ __forceinline__ void attn_unit(long rowbase,int NT,int q0,const bf16*Qh,const bf16*Kc,const bf16*Vc,bf16*Oh,char*shm,const float*rope,const float*qn){
;   int tid_l=threadIdx.x; asm volatile("":"+v"(tid_l)); const int tid=tid_l,lane=tid&63,r32=lane&31,hi=lane>>5; const int wid=__builtin_amdgcn_readfirstlane(tid>>6);
;   const bf16*Qw=Qh+(rowbase+q0+wid*QBLK)*PQ;
;   const bf16*Kh=Kc+rowbase*PQ,*Vh=Vc+rowbase*PQ;
;   const unsigned lds0=(unsigned)(uintptr_t)shm;
;   float*wsf=(float*)(shm+LDS_WS)+wid*64;
;   const bf16*ksrc=Kh+(long)lane*PQ+wid*8;
;   const bf16*vsrc=Vh+(long)(16*(wid&3)+(lane>>2))*PQ+(wid>>2)*32+(lane&3)*8;
;   const unsigned kdst=lds0+LDS_K+wid*1024, vdst=lds0+LDS_V+wid*1024;
;     ...
;   const int vb0=(int)(lds0+LDS_V)+((lane>>4)&1)*32+(lane&3)*8+(4*hi+((lane&15)>>2))*64;
;   const char*Kbase=shm+LDS_K; bf16x8 kf[8];
;   const lds_cptr shm3=(lds_cptr)shm; const lds_cptr kp0=shm3+LDS_K+hi*1024+r32*16; const lds_cptr vp0=shm3+LDS_V+((lane>>4)&1)*32+(lane&3)*8+(4*hi+((lane&15)>>2))*64;
;   DMA_K(0,0);DMA_V(0,0);DMA_K(1,SLOTB);
;   bf16x8 qr[4];
;   #pragma unroll
;   for(int d0=0;d0<4;++d0)qr[d0]=*reinterpret_cast<const bf16x8*>(&Qw[(long)r32*PQ+d0*16+hi*8]);
;   { float qf[4][8]; float ss=0.f;
;     #pragma unroll
;     for(int d0=0;d0<4;++d0){
;       #pragma unroll
;       for(int i=0;i<8;++i){ qf[d0][i]=__uint_as_float(((unsigned)(unsigned short)qr[d0][i])<<16); ss+=qf[d0][i]*qf[d0][i]; } }
;     { auto rr=__builtin_amdgcn_permlane32_swap(__float_as_uint(ss),__float_as_uint(ss),false,false); ss=__uint_as_float(rr[0])+__uint_as_float(rr[1]); }
;     const float rn=1.f/sqrtf(ss*(1.f/64.f)+1e-6f);
;     const float*rp=rope+((long)(q0+wid*QBLK+r32)*32+hi*4)*2;
;     #pragma unroll
;     for(int d0=0;d0<4;++d0){
;       const f32x4_t c01=*reinterpret_cast<const f32x4_t*>(rp+d0*16), c23=*reinterpret_cast<const f32x4_t*>(rp+d0*16+4);
;       const f32x4_t g03=*reinterpret_cast<const f32x4_t*>(qn+d0*16+hi*8), g47=*reinterpret_cast<const f32x4_t*>(qn+d0*16+hi*8+4);
.LBB0_294:
	s_lshl_b32 s61, s30, 8
	s_lshl_b32 s4, s1, 6
	s_lshl_b32 s1, s1, 7
	s_add_u32 s1, s12, s1
	s_addc_u32 s37, s13, 0
	s_lshl_b32 s0, s0, 7
	s_add_u32 s41, s6, s0
	s_addc_u32 s42, s7, 0
	v_mov_b32_e32 v42, v230
	s_add_u32 s0, s56, s0
	s_addc_u32 s43, s57, 0
	v_readfirstlane_b32 s50, v42
	s_ashr_i32 s5, s50, 6
	s_add_u32 s30, s38, s61
	s_addc_u32 s31, s39, 0
	s_lshl_b32 s40, s5, 5
	s_ashr_i32 s35, s40, 31
	s_add_u32 s34, s30, s40
	s_addc_u32 s35, s31, s35
	s_mul_i32 s36, s35, 0x1200
	s_mul_hi_u32 s51, s34, 0x1200
	s_add_i32 s51, s51, s36
	s_mul_i32 s36, s34, 0x1200
	s_add_u32 s36, s1, s36
	s_mul_i32 s1, s39, 0x1200
	s_mul_hi_u32 s39, s38, 0x1200
	s_addc_u32 s37, s37, s51
	s_add_i32 s1, s39, s1
	s_mul_i32 s51, s38, 0x1200
	v_and_b32_e32 v243, 63, v42
	s_add_u32 s38, s41, s51
	s_addc_u32 s39, s42, s1
	v_mul_u32_u24_e32 v0, 0x900, v243
	s_add_u32 s42, s0, s51
	v_lshlrev_b32_e32 v188, 1, v0
	s_addc_u32 s43, s43, s1
	v_lshl_add_u64 v[0:1], s[38:39], 0, v[188:189]
	s_lshl_b32 s38, s5, 3
	s_ashr_i32 s39, s38, 31
	v_lshl_add_u64 v[80:81], s[38:39], 1, v[0:1]
	s_lshl_b32 s0, s5, 4
	v_bfe_u32 v0, v42, 2, 4
	v_and_or_b32 v0, s0, 48, v0
	s_ashr_i32 s0, s50, 3
	s_and_b32 s38, s0, 0xffffffe0
	s_and_b32 s1, s50, 0x3fffffc0
	v_mul_u32_u24_e32 v0, 0x900, v0
	s_ashr_i32 s39, s38, 31
	s_lshl_b32 s68, s5, 10
	v_lshlrev_b32_e32 v188, 1, v0
	v_lshlrev_b32_e32 v244, 3, v42
	s_cmp_lg_u32 0, -1
	v_lshl_add_u64 v[0:1], s[42:43], 0, v[188:189]
	v_and_b32_e32 v247, 24, v244
	s_cselect_b32 s0, 0, 0
	v_lshl_add_u64 v[0:1], s[38:39], 1, v[0:1]
	v_lshlrev_b32_e32 v188, 1, v247
	s_add_i32 s68, s68, s0
	s_mov_b32 s0, m0
	s_mov_b32 m0, s68
	s_nop 0
	global_load_lds_dwordx4 v[80:81], off
	s_mov_b32 m0, s0
	v_and_b32_e32 v245, 31, v42
	v_bfe_u32 v246, v42, 5, 1
	v_lshl_add_u64 v[82:83], v[0:1], 0, v[188:189]
	s_add_i32 s69, s68, 0x6000
	s_mov_b32 s0, m0
	s_mov_b32 m0, s69
	s_nop 0
	global_load_lds_dwordx4 v[82:83], off
	s_mov_b32 m0, s0
	v_lshl_add_u64 v[0:1], v[80:81], 0, s[66:67]
	s_add_i32 s0, s68, 0x2000
	s_mov_b32 s38, m0
	s_mov_b32 m0, s0
	s_nop 0
	global_load_lds_dwordx4 v[0:1], off
	s_mov_b32 m0, s38
	v_mul_u32_u24_e32 v0, 0x900, v245
	v_lshlrev_b32_e32 v84, 4, v246
	v_lshl_or_b32 v0, v0, 1, v84
	global_load_dwordx4 v[16:19], v0, s[36:37]
	global_load_dwordx4 v[20:23], v0, s[36:37] offset:32
	global_load_dwordx4 v[24:27], v0, s[36:37] offset:64
	global_load_dwordx4 v[30:33], v0, s[36:37] offset:96
	v_lshlrev_b32_e32 v0, 1, v42
	v_and_b32_e32 v248, 32, v0
	v_or_b32_e32 v0, s61, v245
	v_add_u32_e32 v0, s40, v0
	v_ashrrev_i32_e32 v1, 31, v0
	v_lshlrev_b64 v[0:1], 8, v[0:1]
	v_lshl_add_u64 v[0:1], s[16:17], 0, v[0:1]
	v_and_b32_e32 v188, 32, v42
	v_lshl_add_u64 v[28:29], v[0:1], 0, v[188:189]
	global_load_dwordx4 v[0:3], v[28:29], off offset:16
	global_load_dwordx4 v[8:11], v[28:29], off
	global_load_dwordx4 v[4:7], v188, s[20:21] offset:16
	global_load_dwordx4 v[12:15], v188, s[20:21]
	v_lshlrev_b32_e32 v44, 4, v245
	s_mov_b64 s[50:51], 0xd8000
	s_lshl_b32 s1, s1, 2
	s_add_i32 s1, s1, 0
	s_mov_b32 s42, 5
	s_mov_b32 s70, 1
	s_mov_b32 s0, 0
	s_movk_i32 s43, 0x2000
	v_mov_b32_e32 v237, 0
	s_movk_i32 s38, 0x4000
	s_add_i32 s39, s64, -5
	v_lshl_add_u32 v250, v245, 2, s1
	v_add_u32_e32 v249, s1, v84
	v_lshl_add_u64 v[180:181], v[82:83], 0, s[50:51]
	s_waitcnt vmcnt(7)
	v_lshlrev_b32_e32 v43, 16, v16
	v_and_b32_e32 v16, 0xffff0000, v16
	v_lshlrev_b32_e32 v54, 16, v17
	v_and_b32_e32 v55, 0xffff0000, v17
	v_mul_f32_e32 v17, v16, v16
	v_fmac_f32_e32 v17, v43, v43
	v_fmac_f32_e32 v17, v54, v54
	v_lshlrev_b32_e32 v56, 16, v18
	v_fmac_f32_e32 v17, v55, v55
	v_and_b32_e32 v57, 0xffff0000, v18
	v_fmac_f32_e32 v17, v56, v56
	v_lshlrev_b32_e32 v58, 16, v19
	v_fmac_f32_e32 v17, v57, v57
	v_and_b32_e32 v59, 0xffff0000, v19
	v_fmac_f32_e32 v17, v58, v58
	s_waitcnt vmcnt(6)
	v_lshlrev_b32_e32 v60, 16, v20
	v_fmac_f32_e32 v17, v59, v59
	v_and_b32_e32 v61, 0xffff0000, v20
	v_fmac_f32_e32 v17, v60, v60
	v_lshlrev_b32_e32 v62, 16, v21
	v_fmac_f32_e32 v17, v61, v61
	v_and_b32_e32 v63, 0xffff0000, v21
	s_waitcnt vmcnt(5)
	v_lshlrev_b32_e32 v68, 16, v24
	v_and_b32_e32 v69, 0xffff0000, v24
	v_fmac_f32_e32 v17, v62, v62
	v_lshlrev_b32_e32 v70, 16, v25
	v_and_b32_e32 v71, 0xffff0000, v25
	v_lshlrev_b32_e32 v72, 16, v26
	v_and_b32_e32 v73, 0xffff0000, v26
	v_lshlrev_b32_e32 v74, 16, v27
	v_and_b32_e32 v75, 0xffff0000, v27
	s_waitcnt vmcnt(4)
; __device__ __forceinline__ unsigned cvtpk_s(float lo,float hi){f32x2_t v={lo,hi};bf16x2_t b=__builtin_convertvector(v,bf16x2_t);return __builtin_bit_cast(unsigned,b);}
; template<int THRL> __device__ __forceinline__ void attn_unit(long rowbase,int NT,int q0,const bf16*Qh,const bf16*Kc,const bf16*Vc,bf16*Oh,char*shm,const float*rope,const float*qn){
;     ...
;       for(int i=0;i<8;++i){ qf[d0][i]=__uint_as_float(((unsigned)(unsigned short)qr[d0][i])<<16); ss+=qf[d0][i]*qf[d0][i]; } }
;     { auto rr=__builtin_amdgcn_permlane32_swap(__float_as_uint(ss),__float_as_uint(ss),false,false); ss=__uint_as_float(rr[0])+__uint_as_float(rr[1]); }
;     const float rn=1.f/sqrtf(ss*(1.f/64.f)+1e-6f);
;     const float*rp=rope+((long)(q0+wid*QBLK+r32)*32+hi*4)*2;
;     #pragma unroll
;     for(int d0=0;d0<4;++d0){
;       const f32x4_t c01=*reinterpret_cast<const f32x4_t*>(rp+d0*16), c23=*reinterpret_cast<const f32x4_t*>(rp+d0*16+4);
;       const f32x4_t g03=*reinterpret_cast<const f32x4_t*>(qn+d0*16+hi*8), g47=*reinterpret_cast<const f32x4_t*>(qn+d0*16+hi*8+4);
;       const float cs_[4]={c01[0],c01[2],c23[0],c23[2]}, sn_[4]={c01[1],c01[3],c23[1],c23[3]}, gg[8]={g03[0],g03[1],g03[2],g03[3],g47[0],g47[1],g47[2],g47[3]};
;       unsigned w[4];
;       #pragma unroll
;       for(int j=0;j<4;++j){ const float y0=qf[d0][2*j]*rn*gg[2*j], y1=qf[d0][2*j+1]*rn*gg[2*j+1];
;         w[j]=cvtpk_s((y0*cs_[j]-y1*sn_[j])*C2,(y0*sn_[j]+y1*cs_[j])*C2); }
;       qr[d0]=__builtin_bit_cast(bf16x8,(u32x4){w[0],w[1],w[2],w[3]}); } }
	v_lshlrev_b32_e32 v76, 16, v30
	v_and_b32_e32 v77, 0xffff0000, v30
	v_lshlrev_b32_e32 v78, 16, v31
	v_and_b32_e32 v79, 0xffff0000, v31
	v_lshlrev_b32_e32 v37, 16, v32
	v_and_b32_e32 v36, 0xffff0000, v32
	v_lshlrev_b32_e32 v34, 16, v33
	v_and_b32_e32 v35, 0xffff0000, v33
	global_load_dwordx4 v[24:27], v188, s[20:21] offset:80
	global_load_dwordx4 v[30:33], v188, s[20:21] offset:64
	v_lshlrev_b32_e32 v64, 16, v22
	v_and_b32_e32 v65, 0xffff0000, v22
	v_lshlrev_b32_e32 v66, 16, v23
	v_and_b32_e32 v67, 0xffff0000, v23
	v_fmac_f32_e32 v17, v63, v63
	global_load_dwordx4 v[20:23], v[28:29], off offset:80
	global_load_dwordx4 v[38:41], v[28:29], off offset:64
	v_fmac_f32_e32 v17, v64, v64
	v_fmac_f32_e32 v17, v65, v65
	v_fmac_f32_e32 v17, v66, v66
	v_fmac_f32_e32 v17, v67, v67
	v_fmac_f32_e32 v17, v68, v68
	v_fmac_f32_e32 v17, v69, v69
	v_fmac_f32_e32 v17, v70, v70
	v_fmac_f32_e32 v17, v71, v71
	v_fmac_f32_e32 v17, v72, v72
	v_fmac_f32_e32 v17, v73, v73
	v_fmac_f32_e32 v17, v74, v74
	v_fmac_f32_e32 v17, v75, v75
	v_fmac_f32_e32 v17, v76, v76
	v_fmac_f32_e32 v17, v77, v77
	v_fmac_f32_e32 v17, v78, v78
	v_fmac_f32_e32 v17, v79, v79
	v_fmac_f32_e32 v17, v37, v37
	v_fmac_f32_e32 v17, v36, v36
	v_fmac_f32_e32 v17, v34, v34
	v_fmac_f32_e32 v17, v35, v35
	v_mov_b32_e32 v18, v17
	s_nop 1
	v_permlane32_swap_b32_e32 v17, v18
	v_add_f32_e32 v17, v17, v18
	v_fmamk_f32 v17, v17, 0x3c800000, v232
	v_mul_f32_e32 v18, 0x4f800000, v17
	v_cmp_gt_f32_e32 vcc, s11, v17
	v_lshlrev_b32_e32 v19, 4, v42
	v_and_b32_e32 v85, 0xc0, v19
	v_cndmask_b32_e32 v17, v17, v18, vcc
	v_sqrt_f32_e32 v18, v17
	s_nop 0
	v_add_u32_e32 v19, -1, v18
	v_fma_f32 v42, -v19, v18, v17
	v_cmp_ge_f32_e64 s[40:41], 0, v42
	v_add_u32_e32 v42, 1, v18
	s_nop 0
	v_cndmask_b32_e64 v19, v18, v19, s[40:41]
	v_fma_f32 v18, -v42, v18, v17
	v_cmp_lt_f32_e64 s[40:41], 0, v18
	s_nop 1
	v_cndmask_b32_e64 v18, v19, v42, s[40:41]
	v_mul_f32_e32 v19, 0x37800000, v18
	v_cndmask_b32_e32 v18, v18, v19, vcc
	v_cmp_class_f32_e32 vcc, v17, v231
	v_lshlrev_b32_e32 v42, 10, v246
	v_add3_u32 v251, 0, v42, v44
	v_cndmask_b32_e32 v17, v18, v17, vcc
	v_div_scale_f32 v18, s[36:37], v17, v17, 1.0
	v_rcp_f32_e32 v19, v18
	s_add_i32 s36, s68, 0x4000
	v_cmp_gt_u32_e64 s[40:41], 32, v243
	v_fma_f32 v42, -v18, v19, 1.0
	v_fmac_f32_e32 v19, v42, v19
	v_div_scale_f32 v42, vcc, 1.0, v17, 1.0
	v_mul_f32_e32 v44, v42, v19
	v_fma_f32 v45, -v18, v44, v42
	v_fmac_f32_e32 v44, v45, v19
	v_fma_f32 v18, -v18, v44, v42
	v_div_fmas_f32 v18, v18, v19, v44
	v_div_fixup_f32 v86, v18, v17, 1.0
	v_mul_f32_e32 v16, v86, v16
	v_mul_f32_e32 v17, v86, v43
	s_waitcnt vmcnt(4)
	v_mul_f32_e32 v16, v13, v16
	v_mul_f32_e32 v12, v12, v17
	v_pk_mul_f32 v[16:17], v[8:9], v[16:17] op_sel:[1,0] op_sel_hi:[0,0]
	v_pk_fma_f32 v[18:19], v[8:9], v[12:13], v[16:17] neg_lo:[0,0,1] neg_hi:[0,0,1]
	v_pk_fma_f32 v[8:9], v[8:9], v[12:13], v[16:17] op_sel_hi:[1,0,1]
	global_load_dwordx4 v[42:45], v188, s[20:21] offset:144
	global_load_dwordx4 v[46:49], v188, s[20:21] offset:128
	v_mov_b32_e32 v19, v9
	v_pk_mul_f32 v[8:9], v[18:19], s[88:89] op_sel_hi:[1,0]
	global_load_dwordx4 v[16:19], v[28:29], off offset:144
	global_load_dwordx4 v[50:53], v[28:29], off offset:128
	v_cvt_pk_bf16_f32 v116, v8, v9
	v_mul_f32_e32 v9, v86, v55
	v_mul_f32_e32 v8, v86, v54
	v_mul_f32_e32 v12, v15, v9
	v_mul_f32_e32 v8, v14, v8
	v_pk_mul_f32 v[12:13], v[10:11], v[12:13] op_sel:[1,0] op_sel_hi:[0,0]
	v_pk_fma_f32 v[14:15], v[10:11], v[8:9], v[12:13] neg_lo:[0,0,1] neg_hi:[0,0,1]
	v_pk_fma_f32 v[8:9], v[10:11], v[8:9], v[12:13] op_sel_hi:[1,0,1]
	s_nop 0
	v_mov_b32_e32 v15, v9
	v_pk_mul_f32 v[8:9], v[14:15], s[88:89] op_sel_hi:[1,0]
	s_nop 0
	v_cvt_pk_bf16_f32 v117, v8, v9
	v_mul_f32_e32 v8, v86, v56
	v_mul_f32_e32 v4, v4, v8
	v_mul_f32_e32 v8, v86, v57
	v_mul_f32_e32 v8, v5, v8
	v_pk_mul_f32 v[8:9], v[0:1], v[8:9] op_sel:[1,0] op_sel_hi:[0,0]
	v_pk_fma_f32 v[10:11], v[0:1], v[4:5], v[8:9] neg_lo:[0,0,1] neg_hi:[0,0,1]
	v_pk_fma_f32 v[0:1], v[0:1], v[4:5], v[8:9] op_sel_hi:[1,0,1]
	s_nop 0
	v_mov_b32_e32 v11, v1
	v_pk_mul_f32 v[0:1], v[10:11], s[88:89] op_sel_hi:[1,0]
	s_nop 0
	v_cvt_pk_bf16_f32 v118, v0, v1
	v_mul_f32_e32 v1, v86, v59
	v_mul_f32_e32 v0, v86, v58
	v_mul_f32_e32 v4, v7, v1
	v_mul_f32_e32 v0, v6, v0
	v_pk_mul_f32 v[4:5], v[2:3], v[4:5] op_sel:[1,0] op_sel_hi:[0,0]
	v_pk_fma_f32 v[6:7], v[2:3], v[0:1], v[4:5] neg_lo:[0,0,1] neg_hi:[0,0,1]
	v_pk_fma_f32 v[0:1], v[2:3], v[0:1], v[4:5] op_sel_hi:[1,0,1]
	s_nop 0
	v_mov_b32_e32 v7, v1
	v_pk_mul_f32 v[0:1], v[6:7], s[88:89] op_sel_hi:[1,0]
	s_nop 0
	v_cvt_pk_bf16_f32 v119, v0, v1
	v_mul_f32_e32 v1, v86, v61
	v_mul_f32_e32 v0, v86, v60
	s_waitcnt vmcnt(6)
	v_mul_f32_e32 v2, v1, v31
	v_mul_f32_e32 v0, v0, v30
	s_waitcnt vmcnt(4)
; __device__ __forceinline__ unsigned cvtpk_s(float lo,float hi){f32x2_t v={lo,hi};bf16x2_t b=__builtin_convertvector(v,bf16x2_t);return __builtin_bit_cast(unsigned,b);}
; #define WAIT_BAR(N) asm volatile("s_waitcnt vmcnt(" #N ") lgkmcnt(0)\n\ts_barrier":::"memory")
;   #define DMA_K(t,slot) glds16(ksrc+(long)(t)*KVBLK*PQ,(unsigned)__builtin_amdgcn_readfirstlane(kdst+(slot)))
; template<int THRL> __device__ __forceinline__ void attn_unit(long rowbase,int NT,int q0,const bf16*Qh,const bf16*Kc,const bf16*Vc,bf16*Oh,char*shm,const float*rope,const float*qn){
;     ...
;       for(int j=0;j<4;++j){ const float y0=qf[d0][2*j]*rn*gg[2*j], y1=qf[d0][2*j+1]*rn*gg[2*j+1];
;         w[j]=cvtpk_s((y0*cs_[j]-y1*sn_[j])*C2,(y0*sn_[j]+y1*cs_[j])*C2); }
;       qr[d0]=__builtin_bit_cast(bf16x8,(u32x4){w[0],w[1],w[2],w[3]}); } }
;   float mhat=0.f,l_reg=0.f;f32x16 o[2];f32x16 negm;
;   { float zz=0.f; asm volatile("":"+v"(zz));
;     _Pragma("unroll") for(int r=0;r<16;++r){o[0][r]=zz;o[1][r]=zz;negm[r]=zz;} }
;   asm volatile("":"+v"(negm));
;     ...
;   bool resc=false;
;     ...
;   f32x16 pA0,pA1,pB0,pB1;
;   int sl_prev=0,sl_cur=0,sl_next=SLOTB;
;     ...
;   DMA_K(2,2*SLOTB);
;   WAIT_BAR(3);
	v_pk_mul_f32 v[2:3], v[38:39], v[2:3] op_sel:[1,0] op_sel_hi:[0,0]
	v_pk_fma_f32 v[4:5], v[38:39], v[0:1], v[2:3] neg_lo:[0,0,1] neg_hi:[0,0,1]
	v_pk_fma_f32 v[0:1], v[38:39], v[0:1], v[2:3] op_sel_hi:[1,0,1]
	s_nop 0
	v_mov_b32_e32 v5, v1
	v_pk_mul_f32 v[0:1], v[4:5], s[88:89] op_sel_hi:[1,0]
	s_nop 0
	v_cvt_pk_bf16_f32 v112, v0, v1
	v_mul_f32_e32 v1, v86, v63
	v_mul_f32_e32 v0, v86, v62
	v_mul_f32_e32 v2, v1, v33
	v_mul_f32_e32 v0, v0, v32
	v_pk_mul_f32 v[2:3], v[40:41], v[2:3] op_sel:[1,0] op_sel_hi:[0,0]
	v_pk_fma_f32 v[4:5], v[40:41], v[0:1], v[2:3] neg_lo:[0,0,1] neg_hi:[0,0,1]
	v_pk_fma_f32 v[0:1], v[40:41], v[0:1], v[2:3] op_sel_hi:[1,0,1]
	global_load_dwordx4 v[38:41], v188, s[20:21] offset:208
	global_load_dwordx4 v[54:57], v188, s[20:21] offset:192
	v_mov_b32_e32 v5, v1
	v_pk_mul_f32 v[0:1], v[4:5], s[88:89] op_sel_hi:[1,0]
	v_lshl_or_b32 v188, v246, 8, v85
	v_cvt_pk_bf16_f32 v113, v0, v1
	v_mul_f32_e32 v0, v86, v64
	v_mul_f32_e32 v1, v86, v65
	global_load_dwordx4 v[58:61], v[28:29], off offset:208
	global_load_dwordx4 v[62:65], v[28:29], off offset:192
	v_mul_f32_e32 v2, v1, v25
	v_mul_f32_e32 v0, v0, v24
	v_pk_mul_f32 v[2:3], v[20:21], v[2:3] op_sel:[1,0] op_sel_hi:[0,0]
	v_pk_fma_f32 v[4:5], v[20:21], v[0:1], v[2:3] neg_lo:[0,0,1] neg_hi:[0,0,1]
	v_pk_fma_f32 v[0:1], v[20:21], v[0:1], v[2:3] op_sel_hi:[1,0,1]
	s_nop 0
	v_mov_b32_e32 v5, v1
	v_pk_mul_f32 v[0:1], v[4:5], s[88:89] op_sel_hi:[1,0]
	s_nop 0
	v_cvt_pk_bf16_f32 v114, v0, v1
	v_mul_f32_e32 v1, v86, v67
	v_mul_f32_e32 v0, v86, v66
	v_mul_f32_e32 v2, v1, v27
	v_mul_f32_e32 v0, v0, v26
	v_pk_mul_f32 v[2:3], v[22:23], v[2:3] op_sel:[1,0] op_sel_hi:[0,0]
	v_pk_fma_f32 v[4:5], v[22:23], v[0:1], v[2:3] neg_lo:[0,0,1] neg_hi:[0,0,1]
	v_pk_fma_f32 v[0:1], v[22:23], v[0:1], v[2:3] op_sel_hi:[1,0,1]
	v_lshl_add_u64 v[26:27], v[80:81], 0, s[96:97]
	v_mov_b32_e32 v5, v1
	v_pk_mul_f32 v[0:1], v[4:5], s[88:89] op_sel_hi:[1,0]
	s_nop 0
	v_cvt_pk_bf16_f32 v115, v0, v1
	v_mul_f32_e32 v1, v86, v69
	v_mul_f32_e32 v0, v86, v68
	s_waitcnt vmcnt(6)
	v_mul_f32_e32 v2, v1, v47
	v_mul_f32_e32 v0, v0, v46
	s_waitcnt vmcnt(4)
	v_pk_mul_f32 v[2:3], v[50:51], v[2:3] op_sel:[1,0] op_sel_hi:[0,0]
	v_pk_fma_f32 v[4:5], v[50:51], v[0:1], v[2:3] neg_lo:[0,0,1] neg_hi:[0,0,1]
	v_pk_fma_f32 v[0:1], v[50:51], v[0:1], v[2:3] op_sel_hi:[1,0,1]
	s_nop 0
	v_mov_b32_e32 v5, v1
	v_pk_mul_f32 v[0:1], v[4:5], s[88:89] op_sel_hi:[1,0]
	s_nop 0
	v_cvt_pk_bf16_f32 v120, v0, v1
	v_mul_f32_e32 v1, v86, v71
	v_mul_f32_e32 v0, v86, v70
	v_mul_f32_e32 v2, v1, v49
	v_mul_f32_e32 v0, v0, v48
	v_pk_mul_f32 v[2:3], v[52:53], v[2:3] op_sel:[1,0] op_sel_hi:[0,0]
	v_pk_fma_f32 v[4:5], v[52:53], v[0:1], v[2:3] neg_lo:[0,0,1] neg_hi:[0,0,1]
	v_pk_fma_f32 v[0:1], v[52:53], v[0:1], v[2:3] op_sel_hi:[1,0,1]
	s_nop 0
	v_mov_b32_e32 v5, v1
	v_pk_mul_f32 v[0:1], v[4:5], s[88:89] op_sel_hi:[1,0]
	s_nop 0
	v_cvt_pk_bf16_f32 v121, v0, v1
	v_mul_f32_e32 v1, v86, v73
	v_mul_f32_e32 v0, v86, v72
	v_mul_f32_e32 v2, v1, v43
	v_mul_f32_e32 v0, v0, v42
	v_pk_mul_f32 v[2:3], v[16:17], v[2:3] op_sel:[1,0] op_sel_hi:[0,0]
	v_pk_fma_f32 v[4:5], v[16:17], v[0:1], v[2:3] neg_lo:[0,0,1] neg_hi:[0,0,1]
	v_pk_fma_f32 v[0:1], v[16:17], v[0:1], v[2:3] op_sel_hi:[1,0,1]
	s_nop 0
	v_mov_b32_e32 v5, v1
	v_pk_mul_f32 v[0:1], v[4:5], s[88:89] op_sel_hi:[1,0]
	s_nop 0
	v_cvt_pk_bf16_f32 v122, v0, v1
	v_mul_f32_e32 v0, v86, v74
	v_mul_f32_e32 v20, v0, v44
	v_mul_f32_e32 v0, v86, v75
	v_mul_f32_e32 v0, v0, v45
	v_pk_mul_f32 v[22:23], v[18:19], v[0:1] op_sel:[1,0] op_sel_hi:[0,0]
	v_mov_b32_e32 v0, v189
	v_pk_fma_f32 v[24:25], v[18:19], v[20:21], v[22:23] neg_lo:[0,0,1] neg_hi:[0,0,1]
	v_mov_b32_e32 v2, v0
	v_mov_b32_e32 v3, v0
	v_mov_b32_e32 v4, v0
	v_mov_b32_e32 v5, v0
	v_mov_b32_e32 v6, v0
	v_mov_b32_e32 v7, v0
	v_mov_b32_e32 v8, v0
	v_mov_b32_e32 v9, v0
	v_mov_b32_e32 v10, v0
	v_mov_b32_e32 v11, v0
	v_mov_b32_e32 v12, v0
	v_mov_b32_e32 v13, v0
	v_mov_b32_e32 v14, v0
	v_mov_b32_e32 v15, v0
	v_mov_b32_e32 v1, v0
	v_mov_b64_e32 v[16:17], v[14:15]
	v_mov_b64_e32 v[14:15], v[12:13]
	v_mov_b64_e32 v[12:13], v[10:11]
	v_mov_b64_e32 v[10:11], v[8:9]
	v_mov_b64_e32 v[8:9], v[6:7]
	v_mov_b64_e32 v[6:7], v[4:5]
	v_mov_b64_e32 v[4:5], v[2:3]
	v_mov_b64_e32 v[2:3], v[0:1]
	s_mov_b32 s37, m0
	s_mov_b32 m0, s36
	s_nop 0
	global_load_lds_dwordx4 v[26:27], off
	s_mov_b32 m0, s37
	s_waitcnt vmcnt(3) lgkmcnt(0)
	s_barrier
; __device__ __forceinline__ void qkt(f32x16&p0,f32x16&p1,const char*Kslot,const bf16x8*qr,const f32x16&negm,int r32,int hi){
;   const char*kb=Kslot+hi*1024+r32*16;
;   #pragma unroll
;   for(int d0=0;d0<4;++d0){
;     const bf16x8 b0=*reinterpret_cast<const bf16x8*>(kb+d0*2048);
;     const bf16x8 b1=*reinterpret_cast<const bf16x8*>(kb+d0*2048+512);
;     if(d0==0){p0=__builtin_amdgcn_mfma_f32_32x32x16_bf16(b0,qr[0],negm,0,0,0);p1=__builtin_amdgcn_mfma_f32_32x32x16_bf16(b1,qr[0],negm,0,0,0);}
;     else{p0=__builtin_amdgcn_mfma_f32_32x32x16_bf16(b0,qr[d0],p0,0,0,0);p1=__builtin_amdgcn_mfma_f32_32x32x16_bf16(b1,qr[d0],p1,0,0,0);}}
; }
; __device__ __forceinline__ void kload8(bf16x8*kf,lds_cptr kp){
;   kf[0]=*(const __attribute__((address_space(3))) bf16x8*)(kp);      kf[1]=*(const __attribute__((address_space(3))) bf16x8*)(kp+512);
;   kf[2]=*(const __attribute__((address_space(3))) bf16x8*)(kp+2048); kf[3]=*(const __attribute__((address_space(3))) bf16x8*)(kp+2560);
;   kf[4]=*(const __attribute__((address_space(3))) bf16x8*)(kp+4096); kf[5]=*(const __attribute__((address_space(3))) bf16x8*)(kp+4608);
;   kf[6]=*(const __attribute__((address_space(3))) bf16x8*)(kp+6144); kf[7]=*(const __attribute__((address_space(3))) bf16x8*)(kp+6656);
; }
; __device__ __forceinline__ void kload2(bf16x8*kf,lds_cptr kp,int j){ kf[2*j]=*(const __attribute__((address_space(3))) bf16x8*)(kp+j*2048); kf[2*j+1]=*(const __attribute__((address_space(3))) bf16x8*)(kp+j*2048+512); }
; __device__ __forceinline__ s16x4 vtr(lds_cptr p){ return __builtin_bit_cast(s16x4,__builtin_amdgcn_ds_read_tr16_b64_v4i16((__attribute__((address_space(3))) v4i16_t*)p)); }
; __device__ __forceinline__ float rowmax(const f32x16&p0,const f32x16&p1){
;   float a=max3f(p0[0],p0[1],p1[0]),b=max3f(p0[2],p0[3],p1[1]);a=max3f(a,p1[2],p1[3]);
;   #pragma unroll
;   for(int r=4;r<16;r+=4){a=max3f(a,p0[r],p0[r+1]);b=max3f(b,p0[r+2],p0[r+3]);a=max3f(a,p1[r],p1[r+1]);b=max3f(b,p1[r+2],p1[r+3]);}
;   const float m=max2f(a,b);
;   auto rr=__builtin_amdgcn_permlane32_swap(__float_as_uint(m),__float_as_uint(m),false,false);
;   return max2f(__uint_as_float(rr[0]),__uint_as_float(rr[1]));
; }
; template<int THRL> __device__ __forceinline__ void attn_unit(long rowbase,int NT,int q0,const bf16*Qh,const bf16*Kc,const bf16*Vc,bf16*Oh,char*shm,const float*rope,const float*qn){
;     ...
;   f32x16 pA0,pA1,pB0,pB1;
	ds_read_b128 v[42:45], v251 offset:512
	ds_read_b128 v[46:49], v251
	v_pk_fma_f32 v[18:19], v[18:19], v[20:21], v[22:23] op_sel_hi:[1,0,1]
	v_mul_f32_e32 v1, v86, v76
	v_mov_b32_e32 v25, v19
	s_waitcnt vmcnt(2)
	v_mul_f32_e32 v50, v1, v54
	v_mul_f32_e32 v1, v86, v77
	v_pk_mul_f32 v[18:19], v[24:25], s[88:89] op_sel_hi:[1,0]
	v_mul_f32_e32 v52, v1, v55
	v_cvt_pk_bf16_f32 v123, v18, v19
	s_waitcnt lgkmcnt(0)
	v_mfma_f32_32x32x16_bf16 v[18:33], v[46:49], v[116:119], v[2:17]
	s_waitcnt vmcnt(0)
	v_mul_f32_e64 v46, v63, v52
	v_mul_f32_e64 v47, v62, v52
	v_fma_f32 v48, v62, v50, -v46
	v_fma_f32 v49, v63, v51, -v47
	v_pk_fma_f32 v[46:47], v[62:63], v[50:51], v[46:47] op_sel_hi:[1,0,1]
	v_mul_f32_e32 v1, v86, v78
	v_mov_b32_e32 v49, v47
	v_pk_mul_f32 v[54:55], v[48:49], s[88:89] op_sel_hi:[1,0]
	ds_read_b128 v[46:49], v251 offset:2560
	ds_read_b128 v[50:53], v251 offset:2048
	v_mfma_f32_32x32x16_bf16 v[2:17], v[42:45], v[116:119], v[2:17]
	v_mul_f32_e32 v42, v1, v56
	v_mul_f32_e32 v1, v86, v79
	v_mul_f32_e32 v44, v1, v57
	v_pk_mul_f32 v[44:45], v[64:65], v[44:45] op_sel:[1,0] op_sel_hi:[0,0]
	v_cvt_pk_bf16_f32 v132, v54, v55
	v_pk_fma_f32 v[54:55], v[64:65], v[42:43], v[44:45] neg_lo:[0,0,1] neg_hi:[0,0,1]
	v_pk_fma_f32 v[42:43], v[64:65], v[42:43], v[44:45] op_sel_hi:[1,0,1]
	s_waitcnt lgkmcnt(0)
	v_mfma_f32_32x32x16_bf16 v[18:33], v[50:53], v[112:115], v[18:33]
	v_mov_b32_e32 v55, v43
	v_mul_f32_e64 v42, v54, s88
	v_mul_f32_e64 v43, v55, s88
	v_mul_f32_e32 v1, v86, v37
	v_cvt_pk_bf16_f32 v133, v42, v43
	ds_read_b128 v[42:45], v251 offset:4608
	ds_read_b128 v[50:53], v251 offset:4096
	v_mul_f32_e32 v38, v1, v38
	v_mul_f32_e32 v1, v86, v36
	v_mfma_f32_32x32x16_bf16 v[2:17], v[46:49], v[112:115], v[2:17]
	v_mul_f32_e32 v36, v1, v39
	v_pk_mul_f32 v[36:37], v[58:59], v[36:37] op_sel:[1,0] op_sel_hi:[0,0]
	v_pk_fma_f32 v[46:47], v[58:59], v[38:39], v[36:37] neg_lo:[0,0,1] neg_hi:[0,0,1]
	v_pk_fma_f32 v[36:37], v[58:59], v[38:39], v[36:37] op_sel_hi:[1,0,1]
	v_mul_f32_e32 v1, v86, v34
	v_mov_b32_e32 v47, v37
	v_mul_f32_e32 v38, v1, v40
	s_waitcnt lgkmcnt(0)
	v_mfma_f32_32x32x16_bf16 v[18:33], v[50:53], v[120:123], v[18:33]
	v_mul_f32_e32 v1, v86, v35
	v_mul_f32_e64 v36, v46, s88
	v_mul_f32_e64 v37, v47, s88
	v_mul_f32_e32 v40, v1, v41
	v_cvt_pk_bf16_f32 v134, v36, v37
	ds_read_b128 v[34:37], v251 offset:6656
	ds_read_b128 v[46:49], v251 offset:6144
	v_pk_mul_f32 v[40:41], v[60:61], v[40:41] op_sel:[1,0] op_sel_hi:[0,0]
	v_add_u32_e32 v1, 0, v248
	v_mfma_f32_32x32x16_bf16 v[2:17], v[42:45], v[120:123], v[2:17]
	v_fma_f32 v42, v60, v38, -v40
	v_fma_f32 v43, v61, v39, -v41
	v_pk_fma_f32 v[38:39], v[60:61], v[38:39], v[40:41] op_sel_hi:[1,0,1]
	v_add3_u32 v253, v1, v247, v188
	v_mov_b32_e32 v43, v39
	v_pk_mul_f32 v[38:39], v[42:43], s[88:89] op_sel_hi:[1,0]
	v_mov_b32_e32 v1, v0
	v_cvt_pk_bf16_f32 v135, v38, v39
	s_waitcnt lgkmcnt(0)
	s_nop 0
	v_mfma_f32_32x32x16_bf16 v[18:33], v[46:49], v[132:135], v[18:33]
	v_mfma_f32_32x32x16_bf16 v[2:17], v[34:37], v[132:135], v[2:17]
	s_nop 15
	s_nop 7
	s_nop 0
	v_max3_f32 v34, v18, v19, v2
	v_max3_f32 v35, v20, v21, v3
	s_nop 0
	v_max3_f32 v34, v34, v4, v5
	v_max3_f32 v35, v35, v24, v25
	s_nop 0
	v_max3_f32 v34, v34, v22, v23
	v_max3_f32 v35, v35, v8, v9
	s_nop 0
	v_max3_f32 v34, v34, v6, v7
	v_max3_f32 v35, v35, v28, v29
	s_nop 0
	v_max3_f32 v34, v34, v26, v27
	v_max3_f32 v35, v35, v12, v13
	s_nop 0
	v_max3_f32 v34, v34, v10, v11
	v_max3_f32 v35, v35, v32, v33
	s_nop 0
	v_max3_f32 v34, v34, v30, v31
	v_max3_f32 v35, v35, v16, v17
	s_nop 0
	v_max3_f32 v34, v34, v14, v15
	s_nop 0
	v_max_f32_e32 v34, v34, v35
	s_nop 0
	v_mov_b32_e32 v35, v34
	s_nop 1
	v_permlane32_swap_b32_e32 v34, v35
	v_max_f32_e32 v34, v34, v35
	s_nop 0
	v_add_f32_e32 v252, v189, v34
	v_sub_f32_e32 v78, v32, v34
	v_sub_f32_e32 v18, v18, v34
	v_sub_f32_e32 v48, v2, v34
	v_sub_f32_e32 v19, v19, v34
	v_sub_f32_e32 v49, v3, v34
	s_nop 0
	v_xor_b32_e32 v32, 0x80000000, v252
	v_sub_f32_e32 v20, v20, v34
	v_sub_f32_e32 v4, v4, v34
	v_sub_f32_e32 v21, v21, v34
	v_sub_f32_e32 v5, v5, v34
	v_sub_f32_e32 v22, v22, v34
	v_sub_f32_e32 v6, v6, v34
	v_sub_f32_e32 v23, v23, v34
	v_sub_f32_e32 v7, v7, v34
	v_sub_f32_e32 v24, v24, v34
	v_sub_f32_e32 v8, v8, v34
	v_sub_f32_e32 v25, v25, v34
	v_sub_f32_e32 v9, v9, v34
	v_sub_f32_e32 v26, v26, v34
	v_sub_f32_e32 v10, v10, v34
	v_sub_f32_e32 v27, v27, v34
	v_sub_f32_e32 v11, v11, v34
	v_sub_f32_e32 v28, v28, v34
	v_sub_f32_e32 v12, v12, v34
	v_sub_f32_e32 v29, v29, v34
	v_sub_f32_e32 v13, v13, v34
	v_sub_f32_e32 v30, v30, v34
	v_sub_f32_e32 v14, v14, v34
	v_sub_f32_e32 v31, v31, v34
	v_sub_f32_e32 v15, v15, v34
	v_sub_f32_e32 v16, v16, v34
	v_sub_f32_e32 v64, v33, v34
	v_sub_f32_e32 v17, v17, v34
	v_mov_b32_e32 v33, v32
	v_mov_b32_e32 v34, v32
	v_mov_b32_e32 v35, v32
	v_mov_b32_e32 v36, v32
	v_mov_b32_e32 v37, v32
	v_mov_b32_e32 v38, v32
	v_mov_b32_e32 v39, v32
	v_mov_b32_e32 v40, v32
	v_mov_b32_e32 v41, v32
	v_mov_b32_e32 v42, v32
	v_mov_b32_e32 v43, v32
	v_mov_b32_e32 v44, v32
	v_mov_b32_e32 v45, v32
	v_mov_b32_e32 v46, v32
	v_mov_b32_e32 v47, v32
	s_waitcnt vmcnt(0) lgkmcnt(0)
	s_barrier
; #define WAIT_BAR(N) asm volatile("s_waitcnt vmcnt(" #N ") lgkmcnt(0)\n\ts_barrier":::"memory")
;   #define DMA_K(t,slot) glds16(ksrc+(long)(t)*KVBLK*PQ,(unsigned)__builtin_amdgcn_readfirstlane(kdst+(slot)))
;   #define DMA_V(t,slot) glds16(vsrc+(long)(t)*KVBLK*PQ,(unsigned)__builtin_amdgcn_readfirstlane(vdst+(slot)))
;   #define CMASK(P0,P1,t) do{}while(0)
;   #define START(P0,P1) do{ const float rm=rowmax(P0,P1); resc=false; \
;     { const float dl=rm; mhat=fadd_s(mhat,dl); \
;       _Pragma("unroll") for(int r=0;r<16;++r){P0[r]=fsub_s(P0[r],dl);P1[r]=fsub_s(P1[r],dl);} \
;       _Pragma("unroll") for(int r=0;r<16;++r)negm[r]=-mhat; asm volatile("":"+v"(negm)); } \
;     _Pragma("unroll") for(int r=0;r<16;++r)P0[r]=__builtin_amdgcn_exp2f(P0[r]); }while(0)
;   #define ROT() do{sl_prev=sl_cur;sl_cur=sl_next;sl_next=(sl_next==(NSLOT-1)*SLOTB)?0:sl_next+SLOTB;}while(0)
; __device__ __forceinline__ void kload8(bf16x8*kf,lds_cptr kp){
;   kf[0]=*(const __attribute__((address_space(3))) bf16x8*)(kp);      kf[1]=*(const __attribute__((address_space(3))) bf16x8*)(kp+512);
;   kf[2]=*(const __attribute__((address_space(3))) bf16x8*)(kp+2048); kf[3]=*(const __attribute__((address_space(3))) bf16x8*)(kp+2560);
;   kf[4]=*(const __attribute__((address_space(3))) bf16x8*)(kp+4096); kf[5]=*(const __attribute__((address_space(3))) bf16x8*)(kp+4608);
;   kf[6]=*(const __attribute__((address_space(3))) bf16x8*)(kp+6144); kf[7]=*(const __attribute__((address_space(3))) bf16x8*)(kp+6656);
; }
; template<int THRL> __device__ __forceinline__ void attn_unit(long rowbase,int NT,int q0,const bf16*Qh,const bf16*Kc,const bf16*Vc,bf16*Oh,char*shm,const float*rope,const float*qn){
;     ...
;   f32x16 pA0,pA1,pB0,pB1;
;   int sl_prev=0,sl_cur=0,sl_next=SLOTB;
;     ...
;   DMA_K(2,2*SLOTB);
;   WAIT_BAR(3);
;   qkt(pA0,pA1,Kbase,qr,negm,r32,hi);asm volatile("s_nop 15\n\ts_nop 7":"+v"(pA0),"+v"(pA1));CMASK(pA0,pA1,0);
;   START(pA0,pA1);
;   _Pragma("unroll") for(int r=0;r<16;++r)pA1[r]=__builtin_amdgcn_exp2f(pA1[r]);
;   WAIT_BAR(0);
;   DMA_K(3,0);DMA_V(1,SLOTB);
;   ROT();
;   kload8(kf,kp0+sl_cur);
;   WAIT_BAR(2);
	v_lshl_add_u64 v[2:3], v[80:81], 0, s[50:51]
	s_mov_b32 s36, m0
	s_mov_b32 m0, s68
	s_nop 0
	global_load_lds_dwordx4 v[2:3], off
	s_mov_b32 m0, s36
	v_lshl_add_u64 v[2:3], v[82:83], 0, s[66:67]
	s_add_i32 s36, s68, 0x8000
	s_mov_b32 s37, m0
	s_mov_b32 m0, s36
	s_nop 0
	global_load_lds_dwordx4 v[2:3], off
	s_mov_b32 m0, s37
	ds_read_b128 v[172:175], v251 offset:8192
	ds_read_b128 v[168:171], v251 offset:8704
	ds_read_b128 v[164:167], v251 offset:10240
	ds_read_b128 v[160:163], v251 offset:10752
	ds_read_b128 v[156:159], v251 offset:12288
	ds_read_b128 v[152:155], v251 offset:12800
	ds_read_b128 v[148:151], v251 offset:14336
	ds_read_b128 v[144:147], v251 offset:14848
	v_exp_f32_e32 v63, v17
	v_exp_f32_e32 v48, v48
	v_exp_f32_e32 v49, v49
	v_exp_f32_e32 v50, v4
	v_exp_f32_e32 v51, v5
	v_exp_f32_e32 v52, v6
	v_exp_f32_e32 v53, v7
	v_exp_f32_e32 v54, v8
	v_exp_f32_e32 v55, v9
	v_exp_f32_e32 v56, v10
	v_exp_f32_e32 v57, v11
	v_exp_f32_e32 v58, v12
	v_exp_f32_e32 v59, v13
	v_exp_f32_e32 v60, v14
	v_exp_f32_e32 v61, v15
	v_exp_f32_e32 v62, v16
	v_exp_f32_e32 v79, v64
	v_exp_f32_e32 v64, v18
	v_exp_f32_e32 v65, v19
	v_exp_f32_e32 v66, v20
	v_exp_f32_e32 v67, v21
	v_exp_f32_e32 v68, v22
	v_exp_f32_e32 v69, v23
	v_exp_f32_e32 v70, v24
	v_exp_f32_e32 v71, v25
	v_exp_f32_e32 v72, v26
	v_exp_f32_e32 v73, v27
	v_exp_f32_e32 v74, v28
	v_exp_f32_e32 v75, v29
	v_exp_f32_e32 v76, v30
	v_exp_f32_e32 v77, v31
	v_exp_f32_e32 v78, v78
	s_mov_b64 s[36:37], 0x168000
	s_waitcnt vmcnt(2) lgkmcnt(0)
	s_barrier
	v_lshl_add_u64 v[182:183], v[80:81], 0, s[36:37]
	s_mov_b64 s[36:37], 0x120000
	v_lshl_add_u64 v[228:229], v[82:83], 0, s[36:37]
	s_mov_b64 s[36:37], 0x1f8000
	v_mov_b32_e32 v2, v0
	v_mov_b32_e32 v3, v0
	v_mov_b32_e32 v4, v0
	v_mov_b32_e32 v5, v0
	v_mov_b32_e32 v6, v0
	v_mov_b32_e32 v7, v0
	v_mov_b32_e32 v8, v0
	v_mov_b32_e32 v9, v0
	v_mov_b32_e32 v10, v0
	v_mov_b32_e32 v11, v0
	v_mov_b32_e32 v12, v0
	v_mov_b32_e32 v13, v0
	v_mov_b32_e32 v14, v0
	v_mov_b32_e32 v15, v0
	v_mov_b32_e32 v16, v0
	v_mov_b32_e32 v17, v0
	v_mov_b32_e32 v18, v0
	v_mov_b32_e32 v19, v0
	v_mov_b32_e32 v20, v0
	v_mov_b32_e32 v21, v0
	v_mov_b32_e32 v22, v0
	v_mov_b32_e32 v23, v0
	v_mov_b32_e32 v24, v0
	v_mov_b32_e32 v25, v0
	v_mov_b32_e32 v26, v0
	v_mov_b32_e32 v27, v0
	v_mov_b32_e32 v28, v0
	v_mov_b32_e32 v29, v0
	v_mov_b32_e32 v30, v0
	v_mov_b32_e32 v31, v0
	v_lshl_add_u64 v[226:227], v[80:81], 0, s[36:37]
	.p2alignl 6, 3212836864

; template <class Epi, class Sched, bool ALIGN_EPI = false, bool SP2 = false>
; __device__ __forceinline__ void gemm_phase(PG8_LAS unsigned char* lds, const Gemm g, const Sched& S, const Epi& E) {
;     ...
;     for (;;) {
;         const bool has_next = S.next(ui + 1, nxt);
;         const char* nA = has_next ? (const char*)g.A + (size_t)nxt.pm * tstep : cA; const char* nB = has_next ? (const char*)g.Bt + (size_t)nxt.pn * tstep : cB;
;         for (int t = 0; t < nt; t += 2) {
;             const bool last = (t == nt - 2);
;             const char* a1 = cA + (size_t)(t + 1) * kstep;
;             const char* a2 = last ? nA : cA + (size_t)(t + 2) * kstep; const char* b2 = last ? nB : cB + (size_t)(t + 2) * kstep;
;             const char* a3 = a2 + kstep; const char* b3 = b2 + kstep;
;     ...
; #pragma unroll
;         for (int a = 0; a < 2; ++a)
; #pragma unroll
;             for (int b = 0; b < 2; ++b)
; #pragma unroll
;                 for (int m = 0; m < 4; ++m)
; #pragma unroll
;                     for (int n = 0; n < 2; ++n) acc[a][b][m][n] = (f32x4){0.f, 0.f, 0.f, 0.f};
;         cur = nxt; cA = nA; cB = nB; ++ui;
.LBB0_576:
	s_ashr_i32 s29, s28, 31
	s_lshl_b64 s[0:1], s[28:29], 19
	s_add_u32 s30, s7, s0
	s_addc_u32 s31, s50, s1
	s_and_b64 s[0:1], s[46:47], exec
	s_cselect_b32 s0, s31, s37
	s_cselect_b32 s1, s30, s36
	s_ashr_i32 s27, s26, 31
	s_lshl_b64 s[4:5], s[26:27], 19
	s_add_u32 s34, s51, s4
	s_addc_u32 s35, s52, s5
	s_and_b64 s[4:5], s[46:47], exec
	s_cselect_b32 s4, s35, s39
	s_cselect_b32 s5, s34, s38
	s_add_u32 s36, s36, 0x40080
	s_addc_u32 s37, s37, 0
	s_add_u32 s27, s38, 0x100
	v_mov_b32_e32 v0, 0
	s_addc_u32 s29, s39, 0
	s_mov_b32 s49, -2
	v_mov_b32_e32 v1, v0
	v_mov_b32_e32 v2, v0
	v_mov_b32_e32 v3, v0
	v_mov_b32_e32 v4, v0
	v_mov_b32_e32 v5, v0
	v_mov_b32_e32 v6, v0
	v_mov_b32_e32 v7, v0
	v_mov_b32_e32 v16, v0
	v_mov_b32_e32 v17, v0
	v_mov_b32_e32 v18, v0
	v_mov_b32_e32 v19, v0
	v_mov_b32_e32 v20, v0
	v_mov_b32_e32 v21, v0
	v_mov_b32_e32 v22, v0
	v_mov_b32_e32 v23, v0
	v_mov_b32_e32 v32, v0
	v_mov_b32_e32 v33, v0
	v_mov_b32_e32 v34, v0
	v_mov_b32_e32 v35, v0
	v_mov_b32_e32 v52, v0
	v_mov_b32_e32 v53, v0
	v_mov_b32_e32 v54, v0
	v_mov_b32_e32 v55, v0
	v_mov_b32_e32 v80, v0
	v_mov_b32_e32 v81, v0
	v_mov_b32_e32 v82, v0
	v_mov_b32_e32 v83, v0
	v_mov_b32_e32 v84, v0
	v_mov_b32_e32 v85, v0
	v_mov_b32_e32 v86, v0
	v_mov_b32_e32 v87, v0
	v_mov_b32_e32 v8, v0
	v_mov_b32_e32 v9, v0
	v_mov_b32_e32 v10, v0
	v_mov_b32_e32 v11, v0
	v_mov_b32_e32 v12, v0
	v_mov_b32_e32 v13, v0
	v_mov_b32_e32 v14, v0
	v_mov_b32_e32 v15, v0
	v_mov_b32_e32 v24, v0
	v_mov_b32_e32 v25, v0
	v_mov_b32_e32 v26, v0
	v_mov_b32_e32 v27, v0
	v_mov_b32_e32 v28, v0
	v_mov_b32_e32 v29, v0
	v_mov_b32_e32 v30, v0
	v_mov_b32_e32 v31, v0
	v_mov_b32_e32 v72, v0
	v_mov_b32_e32 v73, v0
	v_mov_b32_e32 v74, v0
	v_mov_b32_e32 v75, v0
	v_mov_b32_e32 v76, v0
	v_mov_b32_e32 v77, v0
	v_mov_b32_e32 v78, v0
	v_mov_b32_e32 v79, v0
	v_mov_b32_e32 v88, v0
	v_mov_b32_e32 v89, v0
	v_mov_b32_e32 v90, v0
	v_mov_b32_e32 v91, v0
	v_mov_b32_e32 v92, v0
	v_mov_b32_e32 v93, v0
	v_mov_b32_e32 v94, v0
	v_mov_b32_e32 v95, v0
	v_mov_b32_e32 v96, v0
	v_mov_b32_e32 v97, v0
	v_mov_b32_e32 v98, v0
	v_mov_b32_e32 v99, v0
	v_mov_b32_e32 v100, v0
	v_mov_b32_e32 v101, v0
	v_mov_b32_e32 v102, v0
	v_mov_b32_e32 v103, v0
	v_mov_b32_e32 v112, v0
	v_mov_b32_e32 v113, v0
	v_mov_b32_e32 v114, v0
	v_mov_b32_e32 v115, v0
	v_mov_b32_e32 v116, v0
	v_mov_b32_e32 v117, v0
	v_mov_b32_e32 v118, v0
	v_mov_b32_e32 v119, v0
	v_mov_b32_e32 v128, v0
	v_mov_b32_e32 v129, v0
	v_mov_b32_e32 v130, v0
	v_mov_b32_e32 v131, v0
	v_mov_b32_e32 v132, v0
	v_mov_b32_e32 v133, v0
	v_mov_b32_e32 v134, v0
	v_mov_b32_e32 v135, v0
	v_mov_b32_e32 v144, v0
	v_mov_b32_e32 v145, v0
	v_mov_b32_e32 v146, v0
	v_mov_b32_e32 v147, v0
	v_mov_b32_e32 v148, v0
	v_mov_b32_e32 v149, v0
	v_mov_b32_e32 v150, v0
	v_mov_b32_e32 v151, v0
	v_mov_b32_e32 v104, v0
	v_mov_b32_e32 v105, v0
	v_mov_b32_e32 v106, v0
	v_mov_b32_e32 v107, v0
	v_mov_b32_e32 v108, v0
	v_mov_b32_e32 v109, v0
	v_mov_b32_e32 v110, v0
	v_mov_b32_e32 v111, v0
	v_mov_b32_e32 v120, v0
	v_mov_b32_e32 v121, v0
	v_mov_b32_e32 v122, v0
	v_mov_b32_e32 v123, v0
	v_mov_b32_e32 v124, v0
	v_mov_b32_e32 v125, v0
	v_mov_b32_e32 v126, v0
	v_mov_b32_e32 v127, v0
	v_mov_b32_e32 v136, v0
	v_mov_b32_e32 v137, v0
	v_mov_b32_e32 v138, v0
	v_mov_b32_e32 v139, v0
	v_mov_b32_e32 v140, v0
	v_mov_b32_e32 v141, v0
	v_mov_b32_e32 v142, v0
	v_mov_b32_e32 v143, v0
	v_mov_b32_e32 v152, v0
	v_mov_b32_e32 v153, v0
	v_mov_b32_e32 v154, v0
	v_mov_b32_e32 v155, v0
	v_mov_b32_e32 v156, v0
	v_mov_b32_e32 v157, v0
	v_mov_b32_e32 v158, v0
	v_mov_b32_e32 v159, v0
	.p2alignl 6, 3212836864

; template <class Epi, class Sched, bool ALIGN_EPI = false, bool SP2 = false>
; __device__ __forceinline__ void gemm_phase(PG8_LAS unsigned char* lds, const Gemm g, const Sched& S, const Epi& E) {
;     ...
;     for (;;) {
;         const bool has_next = S.next(ui + 1, nxt);
;         const char* nA = has_next ? (const char*)g.A + (size_t)nxt.pm * tstep : cA; const char* nB = has_next ? (const char*)g.Bt + (size_t)nxt.pn * tstep : cB;
;         for (int t = 0; t < nt; t += 2) {
;             const bool last = (t == nt - 2);
;             const char* a1 = cA + (size_t)(t + 1) * kstep;
;             const char* a2 = last ? nA : cA + (size_t)(t + 2) * kstep; const char* b2 = last ? nB : cB + (size_t)(t + 2) * kstep;
;             const char* a3 = a2 + kstep; const char* b3 = b2 + kstep;
;     ...
; #pragma unroll
;         for (int a = 0; a < 2; ++a)
; #pragma unroll
;             for (int b = 0; b < 2; ++b)
; #pragma unroll
;                 for (int m = 0; m < 4; ++m)
; #pragma unroll
;                     for (int n = 0; n < 2; ++n) acc[a][b][m][n] = (f32x4){0.f, 0.f, 0.f, 0.f};
;         cur = nxt; cA = nA; cB = nB; ++ui;
.LBB0_665:
	s_ashr_i32 s57, s56, 31
	s_lshl_b64 s[0:1], s[56:57], 19
	s_add_u32 s40, s6, s0
	s_addc_u32 s41, s7, s1
	s_and_b64 s[0:1], s[44:45], exec
	s_cselect_b32 s0, s41, s79
	s_cselect_b32 s1, s40, s78
	s_ashr_i32 s55, s54, 31
	s_lshl_b64 s[4:5], s[54:55], 19
	s_add_u32 s86, s60, s4
	s_addc_u32 s87, s61, s5
	s_and_b64 s[4:5], s[44:45], exec
	s_cselect_b32 s4, s87, s95
	s_cselect_b32 s5, s86, s94
	s_add_u32 s46, s78, 0x40080
	s_addc_u32 s47, s79, 0
	s_add_u32 s55, s94, 0x100
	v_mov_b32_e32 v4, 0
	s_addc_u32 s57, s95, 0
	s_mov_b32 s75, -2
	v_mov_b32_e32 v5, v4
	v_mov_b32_e32 v6, v4
	v_mov_b32_e32 v7, v4
	v_mov_b32_e32 v36, v4
	v_mov_b32_e32 v37, v4
	v_mov_b32_e32 v38, v4
	v_mov_b32_e32 v39, v4
	v_mov_b32_e32 v12, v4
	v_mov_b32_e32 v13, v4
	v_mov_b32_e32 v14, v4
	v_mov_b32_e32 v15, v4
	v_mov_b32_e32 v44, v4
	v_mov_b32_e32 v45, v4
	v_mov_b32_e32 v46, v4
	v_mov_b32_e32 v47, v4
	v_mov_b32_e32 v0, v4
	v_mov_b32_e32 v1, v4
	v_mov_b32_e32 v2, v4
	v_mov_b32_e32 v3, v4
	v_mov_b32_e32 v8, v4
	v_mov_b32_e32 v9, v4
	v_mov_b32_e32 v10, v4
	v_mov_b32_e32 v11, v4
	v_mov_b32_e32 v28, v4
	v_mov_b32_e32 v29, v4
	v_mov_b32_e32 v30, v4
	v_mov_b32_e32 v31, v4
	v_mov_b32_e32 v20, v4
	v_mov_b32_e32 v21, v4
	v_mov_b32_e32 v22, v4
	v_mov_b32_e32 v23, v4
	v_mov_b32_e32 v40, v4
	v_mov_b32_e32 v41, v4
	v_mov_b32_e32 v42, v4
	v_mov_b32_e32 v43, v4
	v_mov_b32_e32 v32, v4
	v_mov_b32_e32 v33, v4
	v_mov_b32_e32 v34, v4
	v_mov_b32_e32 v35, v4
	v_mov_b32_e32 v56, v4
	v_mov_b32_e32 v57, v4
	v_mov_b32_e32 v58, v4
	v_mov_b32_e32 v59, v4
	v_mov_b32_e32 v64, v4
	v_mov_b32_e32 v65, v4
	v_mov_b32_e32 v66, v4
	v_mov_b32_e32 v67, v4
	v_mov_b32_e32 v60, v4
	v_mov_b32_e32 v61, v4
	v_mov_b32_e32 v62, v4
	v_mov_b32_e32 v63, v4
	v_mov_b32_e32 v68, v4
	v_mov_b32_e32 v69, v4
	v_mov_b32_e32 v70, v4
	v_mov_b32_e32 v71, v4
	v_mov_b32_e32 v84, v4
	v_mov_b32_e32 v85, v4
	v_mov_b32_e32 v86, v4
	v_mov_b32_e32 v87, v4
	v_mov_b32_e32 v100, v4
	v_mov_b32_e32 v101, v4
	v_mov_b32_e32 v102, v4
	v_mov_b32_e32 v103, v4
	v_mov_b32_e32 v92, v4
	v_mov_b32_e32 v93, v4
	v_mov_b32_e32 v94, v4
	v_mov_b32_e32 v95, v4
	v_mov_b32_e32 v108, v4
	v_mov_b32_e32 v109, v4
	v_mov_b32_e32 v110, v4
	v_mov_b32_e32 v111, v4
	v_mov_b32_e32 v52, v4
	v_mov_b32_e32 v53, v4
	v_mov_b32_e32 v54, v4
	v_mov_b32_e32 v55, v4
	v_mov_b32_e32 v80, v4
	v_mov_b32_e32 v81, v4
	v_mov_b32_e32 v82, v4
	v_mov_b32_e32 v83, v4
	v_mov_b32_e32 v96, v4
	v_mov_b32_e32 v97, v4
	v_mov_b32_e32 v98, v4
	v_mov_b32_e32 v99, v4
	v_mov_b32_e32 v88, v4
	v_mov_b32_e32 v89, v4
	v_mov_b32_e32 v90, v4
	v_mov_b32_e32 v91, v4
	v_mov_b32_e32 v104, v4
	v_mov_b32_e32 v105, v4
	v_mov_b32_e32 v106, v4
	v_mov_b32_e32 v107, v4
	v_mov_b32_e32 v76, v4
	v_mov_b32_e32 v77, v4
	v_mov_b32_e32 v78, v4
	v_mov_b32_e32 v79, v4
	v_mov_b32_e32 v16, v4
	v_mov_b32_e32 v17, v4
	v_mov_b32_e32 v18, v4
	v_mov_b32_e32 v19, v4
	v_mov_b32_e32 v24, v4
	v_mov_b32_e32 v25, v4
	v_mov_b32_e32 v26, v4
	v_mov_b32_e32 v27, v4
	v_mov_b32_e32 v112, v4
	v_mov_b32_e32 v113, v4
	v_mov_b32_e32 v114, v4
	v_mov_b32_e32 v115, v4
	v_mov_b32_e32 v120, v4
	v_mov_b32_e32 v121, v4
	v_mov_b32_e32 v122, v4
	v_mov_b32_e32 v123, v4
	v_mov_b32_e32 v116, v4
	v_mov_b32_e32 v117, v4
	v_mov_b32_e32 v118, v4
	v_mov_b32_e32 v119, v4
	v_mov_b32_e32 v124, v4
	v_mov_b32_e32 v125, v4
	v_mov_b32_e32 v126, v4
	v_mov_b32_e32 v127, v4
	v_mov_b32_e32 v128, v4
	v_mov_b32_e32 v129, v4
	v_mov_b32_e32 v130, v4
	v_mov_b32_e32 v131, v4
	v_mov_b32_e32 v48, v4
	v_mov_b32_e32 v49, v4
	v_mov_b32_e32 v50, v4
	v_mov_b32_e32 v51, v4
	.p2alignl 6, 3212836864

; template <class Epi, class Sched, bool ALIGN_EPI = false, bool SP2 = false>
; __device__ __forceinline__ void gemm_phase(PG8_LAS unsigned char* lds, const Gemm g, const Sched& S, const Epi& E) {
;     ...
;         for (int t = 0; t < nt; t += 2) {
;             const bool last = (t == nt - 2);
;             const char* a1 = cA + (size_t)(t + 1) * kstep;
;             const char* a2 = last ? nA : cA + (size_t)(t + 2) * kstep; const char* b2 = last ? nB : cB + (size_t)(t + 2) * kstep;
;     ...
; #pragma unroll
;         for (int a = 0; a < 2; ++a)
; #pragma unroll
;             for (int b = 0; b < 2; ++b)
; #pragma unroll
;                 for (int m = 0; m < 4; ++m)
; #pragma unroll
;                     for (int n = 0; n < 2; ++n) acc[a][b][m][n] = (f32x4){0.f, 0.f, 0.f, 0.f};
.LBB0_831:
	s_add_u32 s0, s38, 0x100
	v_mov_b32_e32 v0, 0
	s_addc_u32 s1, s39, 0
	s_mov_b32 s4, -2
	v_mov_b32_e32 v1, v0
	v_mov_b32_e32 v2, v0
	v_mov_b32_e32 v3, v0
	v_mov_b32_e32 v4, v0
	v_mov_b32_e32 v5, v0
	v_mov_b32_e32 v6, v0
	v_mov_b32_e32 v7, v0
	v_mov_b32_e32 v16, v0
	v_mov_b32_e32 v17, v0
	v_mov_b32_e32 v18, v0
	v_mov_b32_e32 v19, v0
	v_mov_b32_e32 v20, v0
	v_mov_b32_e32 v21, v0
	v_mov_b32_e32 v22, v0
	v_mov_b32_e32 v23, v0
	v_mov_b32_e32 v32, v0
	v_mov_b32_e32 v33, v0
	v_mov_b32_e32 v34, v0
	v_mov_b32_e32 v35, v0
	v_mov_b32_e32 v36, v0
	v_mov_b32_e32 v37, v0
	v_mov_b32_e32 v38, v0
	v_mov_b32_e32 v39, v0
	v_mov_b32_e32 v48, v0
	v_mov_b32_e32 v49, v0
	v_mov_b32_e32 v50, v0
	v_mov_b32_e32 v51, v0
	v_mov_b32_e32 v52, v0
	v_mov_b32_e32 v53, v0
	v_mov_b32_e32 v54, v0
	v_mov_b32_e32 v55, v0
	v_mov_b32_e32 v8, v0
	v_mov_b32_e32 v9, v0
	v_mov_b32_e32 v10, v0
	v_mov_b32_e32 v11, v0
	v_mov_b32_e32 v12, v0
	v_mov_b32_e32 v13, v0
	v_mov_b32_e32 v14, v0
	v_mov_b32_e32 v15, v0
	v_mov_b32_e32 v24, v0
	v_mov_b32_e32 v25, v0
	v_mov_b32_e32 v26, v0
	v_mov_b32_e32 v27, v0
	v_mov_b32_e32 v28, v0
	v_mov_b32_e32 v29, v0
	v_mov_b32_e32 v30, v0
	v_mov_b32_e32 v31, v0
	v_mov_b32_e32 v40, v0
	v_mov_b32_e32 v41, v0
	v_mov_b32_e32 v42, v0
	v_mov_b32_e32 v43, v0
	v_mov_b32_e32 v44, v0
	v_mov_b32_e32 v45, v0
	v_mov_b32_e32 v46, v0
	v_mov_b32_e32 v47, v0
	v_mov_b32_e32 v72, v0
	v_mov_b32_e32 v73, v0
	v_mov_b32_e32 v74, v0
	v_mov_b32_e32 v75, v0
	v_mov_b32_e32 v84, v0
	v_mov_b32_e32 v85, v0
	v_mov_b32_e32 v86, v0
	v_mov_b32_e32 v87, v0
	v_mov_b32_e32 v96, v0
	v_mov_b32_e32 v97, v0
	v_mov_b32_e32 v98, v0
	v_mov_b32_e32 v99, v0
	v_mov_b32_e32 v100, v0
	v_mov_b32_e32 v101, v0
	v_mov_b32_e32 v102, v0
	v_mov_b32_e32 v103, v0
	v_mov_b32_e32 v112, v0
	v_mov_b32_e32 v113, v0
	v_mov_b32_e32 v114, v0
	v_mov_b32_e32 v115, v0
	v_mov_b32_e32 v116, v0
	v_mov_b32_e32 v117, v0
	v_mov_b32_e32 v118, v0
	v_mov_b32_e32 v119, v0
	v_mov_b32_e32 v128, v0
	v_mov_b32_e32 v129, v0
	v_mov_b32_e32 v130, v0
	v_mov_b32_e32 v131, v0
	v_mov_b32_e32 v132, v0
	v_mov_b32_e32 v133, v0
	v_mov_b32_e32 v134, v0
	v_mov_b32_e32 v135, v0
	v_mov_b32_e32 v144, v0
	v_mov_b32_e32 v145, v0
	v_mov_b32_e32 v146, v0
	v_mov_b32_e32 v147, v0
	v_mov_b32_e32 v148, v0
	v_mov_b32_e32 v149, v0
	v_mov_b32_e32 v150, v0
	v_mov_b32_e32 v151, v0
	v_mov_b32_e32 v104, v0
	v_mov_b32_e32 v105, v0
	v_mov_b32_e32 v106, v0
	v_mov_b32_e32 v107, v0
	v_mov_b32_e32 v108, v0
	v_mov_b32_e32 v109, v0
	v_mov_b32_e32 v110, v0
	v_mov_b32_e32 v111, v0
	v_mov_b32_e32 v120, v0
	v_mov_b32_e32 v121, v0
	v_mov_b32_e32 v122, v0
	v_mov_b32_e32 v123, v0
	v_mov_b32_e32 v124, v0
	v_mov_b32_e32 v125, v0
	v_mov_b32_e32 v126, v0
	v_mov_b32_e32 v127, v0
	v_mov_b32_e32 v136, v0
	v_mov_b32_e32 v137, v0
	v_mov_b32_e32 v138, v0
	v_mov_b32_e32 v139, v0
	v_mov_b32_e32 v140, v0
	v_mov_b32_e32 v141, v0
	v_mov_b32_e32 v142, v0
	v_mov_b32_e32 v143, v0
	v_mov_b32_e32 v152, v0
	v_mov_b32_e32 v153, v0
	v_mov_b32_e32 v154, v0
	v_mov_b32_e32 v155, v0
	v_mov_b32_e32 v156, v0
	v_mov_b32_e32 v157, v0
	v_mov_b32_e32 v158, v0
	v_mov_b32_e32 v159, v0
	.p2alignl 6, 3212836864
